# speedup vs baseline: 1.0029x; 1.0029x over previous
; __device__ __forceinline__ float bf2f(bf16_t h) { return __uint_as_float(((unsigned)h) << 16); }
; __device__ __forceinline__ int otid() { int t = threadIdx.x; asm volatile("" : "+v"(t)); return t; }
; __device__ __forceinline__ void lru_gate(const Params& p) {
;     ...
;     for (int idx = blockIdx.x * 512 + otid(); idx < total; idx += gridDim.x * 512) {
;         const size_t a = (size_t)idx * 8;
;         uint4 f = *(const uint4*)(YF + a), bk = *(const uint4*)(YB + a), g = *(const uint4*)(Gt + a);
;         unsigned fv[4] = {f.x, f.y, f.z, f.w}, bv[4] = {bk.x, bk.y, bk.z, bk.w}, gv[4] = {g.x, g.y, g.z, g.w};
;         unsigned ov[4];
; #pragma unroll
;         for (int e = 0; e < 4; ++e) {
;             float y0 = bf2f((bf16_t)(fv[e] & 0xFFFF)) + bf2f((bf16_t)(bv[e] & 0xFFFF));
;             float y1 = bf2f((bf16_t)(fv[e] >> 16)) + bf2f((bf16_t)(bv[e] >> 16));
;             float g0 = gelu_tanh(bf2f((bf16_t)(gv[e] & 0xFFFF))), g1 = gelu_tanh(bf2f((bf16_t)(gv[e] >> 16)));
;             ov[e] = pack2(y0 * g0, y1 * g1);
;         }
;         *(uint4*)(YG + a) = make_uint4(ov[0], ov[1], ov[2], ov[3]);
;     }
.LBB0_408:
	s_or_b64 exec, exec, s[0:1]
	v_mov_b32_e32 v2, v166
	v_readlane_b32 s0, v252, 40
	s_barrier
	s_nop 0
	v_add_u32_e32 v14, s0, v2
	s_mov_b32 s0, 0x303000
	v_cmp_gt_i32_e32 vcc, s0, v14
	s_and_saveexec_b64 s[0:1], vcc
	v_readlane_b32 s4, v253, 23
	v_readlane_b32 s8, v253, 25
	v_readlane_b32 s5, v253, 24
	s_mov_b32 s6, 0x302fff
	v_readlane_b32 s9, v253, 26
	s_cbranch_execz .LBB0_411
	s_mov_b64 s[2:3], 0
	v_ashrrev_i32_e32 v15, 31, v14
	v_lshlrev_b64 v[16:17], 4, v[14:15]
	v_lshl_add_u64 v[56:57], s[4:5], 0, v[16:17]
	global_load_dwordx4 v[40:43], v[56:57], off
	v_lshl_add_u64 v[56:57], s[8:9], 0, v[16:17]
	global_load_dwordx4 v[44:47], v[56:57], off
	v_lshl_add_u64 v[56:57], s[16:17], 0, v[16:17]
	global_load_dwordx4 v[48:51], v[56:57], off
	global_load_dword v58, v[56:57], off
.LBB0_410:
	s_waitcnt vmcnt(1)
	v_mov_b32_e32 v6, v40
	v_mov_b32_e32 v7, v41
	v_mov_b32_e32 v8, v42
	v_mov_b32_e32 v9, v43
	v_mov_b32_e32 v10, v44
	v_mov_b32_e32 v11, v45
	v_mov_b32_e32 v12, v46
	v_mov_b32_e32 v13, v47
	v_mov_b32_e32 v2, v48
	v_mov_b32_e32 v3, v49
	v_mov_b32_e32 v4, v50
	v_mov_b32_e32 v5, v51
	v_mov_b32_e32 v52, v16
	v_mov_b32_e32 v53, v17
	v_add_u32_e32 v14, s27, v14
	v_cmp_lt_i32_e32 vcc, s6, v14
	s_or_b64 s[2:3], vcc, s[2:3]
	v_min_i32_e32 v54, s6, v14
	v_ashrrev_i32_e32 v55, 31, v54
	v_lshlrev_b64 v[16:17], 4, v[54:55]
	v_lshl_add_u64 v[56:57], s[4:5], 0, v[16:17]
	global_load_dwordx4 v[40:43], v[56:57], off
	v_lshl_add_u64 v[56:57], s[8:9], 0, v[16:17]
	global_load_dwordx4 v[44:47], v[56:57], off
	v_lshl_add_u64 v[56:57], s[16:17], 0, v[16:17]
	global_load_dwordx4 v[48:51], v[56:57], off
	v_lshlrev_b32_e32 v18, 16, v6
	v_and_b32_e32 v19, 0xffff0000, v6
	v_lshlrev_b32_e32 v20, 16, v10
	v_and_b32_e32 v21, 0xffff0000, v10
	v_lshlrev_b32_e32 v22, 16, v2
	v_and_b32_e32 v23, 0xffff0000, v2
	v_mul_f32_e32 v2, 0x3d372713, v22
	v_mul_f32_e32 v2, v2, v22
	v_mov_b32_e32 v6, v22
	v_fmac_f32_e32 v6, v2, v6
	v_mul_f32_e32 v2, 0xbfcc422a, v6
	v_mul_f32_e32 v2, 0x3fb8aa3b, v2
	v_exp_f32_e32 v2, v2
	v_pk_add_f32 v[18:19], v[18:19], v[20:21]
	v_mov_b32_e32 v6, v23
	v_lshlrev_b32_e32 v10, 16, v11
	v_add_f32_e32 v2, 1.0, v2
	v_rcp_f32_e32 v20, v2
	v_mul_f32_e32 v2, 0x3d372713, v23
	v_mul_f32_e32 v2, v2, v23
	v_fmac_f32_e32 v6, v2, v6
	v_mul_f32_e32 v2, 0xbfcc422a, v6
	v_mul_f32_e32 v2, 0x3fb8aa3b, v2
	v_exp_f32_e32 v2, v2
	v_lshlrev_b32_e32 v6, 16, v7
	v_and_b32_e32 v7, 0xffff0000, v7
	v_and_b32_e32 v11, 0xffff0000, v11
	v_add_f32_e32 v2, 1.0, v2
	v_rcp_f32_e32 v21, v2
	v_pk_add_f32 v[6:7], v[6:7], v[10:11]
	v_pk_mul_f32 v[20:21], v[20:21], v[22:23]
	s_nop 0
	v_pk_mul_f32 v[18:19], v[18:19], v[20:21]
	s_nop 0
	v_cvt_pk_bf16_f32 v2, v18, v19
	v_lshlrev_b32_e32 v18, 16, v3
	v_and_b32_e32 v19, 0xffff0000, v3
	v_mul_f32_e32 v3, 0x3d372713, v18
	v_mul_f32_e32 v3, v3, v18
	v_mov_b32_e32 v10, v18
	v_fmac_f32_e32 v10, v3, v10
	v_mul_f32_e32 v3, 0xbfcc422a, v10
	v_mul_f32_e32 v3, 0x3fb8aa3b, v3
	v_exp_f32_e32 v3, v3
	v_mov_b32_e32 v11, v19
	v_add_f32_e32 v3, 1.0, v3
	v_rcp_f32_e32 v10, v3
	v_mul_f32_e32 v3, 0x3d372713, v19
	v_mul_f32_e32 v3, v3, v19
	v_fmac_f32_e32 v11, v3, v11
	v_mul_f32_e32 v3, 0xbfcc422a, v11
	v_mul_f32_e32 v3, 0x3fb8aa3b, v3
	v_exp_f32_e32 v3, v3
	s_nop 0
	v_add_f32_e32 v3, 1.0, v3
	v_rcp_f32_e32 v11, v3
	s_nop 0
	v_pk_mul_f32 v[10:11], v[10:11], v[18:19]
	v_lshlrev_b32_e32 v18, 16, v4
	v_pk_mul_f32 v[6:7], v[6:7], v[10:11]
	v_and_b32_e32 v19, 0xffff0000, v4
	v_mul_f32_e32 v4, 0x3d372713, v18
	v_cvt_pk_bf16_f32 v3, v6, v7
	v_lshlrev_b32_e32 v6, 16, v8
	v_and_b32_e32 v7, 0xffff0000, v8
	v_mul_f32_e32 v4, v4, v18
	v_mov_b32_e32 v8, v18
	v_fmac_f32_e32 v8, v4, v8
	v_mul_f32_e32 v4, 0xbfcc422a, v8
	v_mul_f32_e32 v4, 0x3fb8aa3b, v4
	v_exp_f32_e32 v4, v4
	v_lshlrev_b32_e32 v10, 16, v12
	v_and_b32_e32 v11, 0xffff0000, v12
	v_pk_add_f32 v[6:7], v[6:7], v[10:11]
	v_add_f32_e32 v4, 1.0, v4
	v_rcp_f32_e32 v10, v4
	v_mul_f32_e32 v4, 0x3d372713, v19
	v_mul_f32_e32 v4, v4, v19
	v_mov_b32_e32 v8, v19
	v_fmac_f32_e32 v8, v4, v8
	v_mul_f32_e32 v4, 0xbfcc422a, v8
	v_mul_f32_e32 v4, 0x3fb8aa3b, v4
	v_exp_f32_e32 v4, v4
	v_lshlrev_b32_e32 v8, 16, v9
	v_and_b32_e32 v9, 0xffff0000, v9
	v_add_f32_e32 v4, 1.0, v4
	v_rcp_f32_e32 v11, v4
	s_nop 0
	v_pk_mul_f32 v[10:11], v[10:11], v[18:19]
	s_nop 0
	v_pk_mul_f32 v[6:7], v[6:7], v[10:11]
	v_lshlrev_b32_e32 v10, 16, v13
	v_cvt_pk_bf16_f32 v4, v6, v7
	v_lshlrev_b32_e32 v6, 16, v5
	v_and_b32_e32 v11, 0xffff0000, v13
	v_and_b32_e32 v7, 0xffff0000, v5
	v_mul_f32_e32 v5, 0x3d372713, v6
	v_pk_add_f32 v[8:9], v[8:9], v[10:11]
	v_mul_f32_e32 v5, v5, v6
	v_mov_b32_e32 v10, v6
	v_fmac_f32_e32 v10, v5, v10
	v_mul_f32_e32 v5, 0xbfcc422a, v10
	v_mul_f32_e32 v5, 0x3fb8aa3b, v5
	v_exp_f32_e32 v5, v5
	v_mov_b32_e32 v11, v7
	v_add_f32_e32 v5, 1.0, v5
	v_rcp_f32_e32 v10, v5
	v_mul_f32_e32 v5, 0x3d372713, v7
	v_mul_f32_e32 v5, v5, v7
	v_fmac_f32_e32 v11, v5, v11
	v_mul_f32_e32 v5, 0xbfcc422a, v11
	v_mul_f32_e32 v5, 0x3fb8aa3b, v5
	v_exp_f32_e32 v5, v5
	s_nop 0
	v_add_f32_e32 v5, 1.0, v5
	v_rcp_f32_e32 v11, v5
	s_nop 0
	v_pk_mul_f32 v[6:7], v[10:11], v[6:7]
	s_nop 0
	v_pk_mul_f32 v[6:7], v[8:9], v[6:7]
	s_nop 0
	v_cvt_pk_bf16_f32 v5, v6, v7
	v_lshl_add_u64 v[6:7], s[38:39], 0, v[52:53]
	global_store_dwordx4 v[6:7], v[2:5], off
	s_andn2_b64 exec, exec, s[2:3]
	s_cbranch_execnz .LBB0_410
